# c13 + GDN staging and tile multiplies as v_pk_mul_f32 (broadcast scales), direction variants instead of v_alignbit; GEMM loop heads pinned at offset 28 mod 64
# baseline (speedup 1.0000x reference)
.LBB0_359:
	s_andn2_b64 vcc, exec, s[10:11]
	s_cbranch_vccnz .LBB0_361
	s_waitcnt lgkmcnt(1)
	v_mul_f32_e32 v124, 0x3fb8aa3b, v147
	v_exp_f32_e32 v124, v124
	s_waitcnt lgkmcnt(0)
	v_mul_f32_e32 v125, 0x3fb8aa3b, v144
	v_sub_f32_e32 v126, s63, v147
	v_exp_f32_e32 v125, v125
	v_mul_f32_e32 v126, 0x3fb8aa3b, v126
	v_exp_f32_e32 v126, v126
	v_sub_f32_e32 v127, s63, v144
	v_mul_f32_e32 v124, v141, v124
	v_mul_f32_e32 v127, 0x3fb8aa3b, v127
	v_exp_f32_e32 v127, v127
	v_mul_f32_e32 v128, v124, v120
	v_mad_u32_u24 v129, v206, s73, v143
	v_mul_f32_e32 v125, v0, v125
	v_cvt_pk_bf16_f32 v128, v128, s0
	v_lshl_add_u32 v129, v129, 1, 0
	ds_write_b128 v145, v[84:87]
	ds_write_b128 v146, v[96:99]
	ds_write_b128 v145, v[88:91] offset:17408
	ds_write_b128 v146, v[100:103] offset:17408
	v_mad_u32_u24 v130, v206, s73, v142
	v_lshl_add_u32 v130, v130, 1, 0
	v_min_u32_e32 v131, v129, v130
	s_cmp_lg_u64 s[4:5], 0
	s_cbranch_scc0 .Lgpk1_rev
	v_pk_mul_f32 v[132:133], v[120:121], v[124:125] op_sel_hi:[1,0]
	v_pk_mul_f32 v[134:135], v[122:123], v[124:125] op_sel:[0,1] op_sel_hi:[1,1]
	v_pk_mul_f32 v[136:137], v[120:121], v[126:127] op_sel_hi:[1,0]
	v_pk_mul_f32 v[138:139], v[122:123], v[126:127] op_sel:[0,1] op_sel_hi:[1,1]
	v_cvt_pk_bf16_f32 v128, v132, v134
	ds_write_b32 v131, v128 offset:34816
	v_cvt_pk_bf16_f32 v129, v136, v138
	ds_write_b32 v131, v129 offset:53248
	v_cvt_pk_bf16_f32 v128, v133, v135
	ds_write_b32 v131, v128 offset:34960
	v_cvt_pk_bf16_f32 v129, v137, v139
	ds_write_b32 v131, v129 offset:53392
	v_pk_mul_f32 v[132:133], v[116:117], v[124:125] op_sel_hi:[1,0]
	v_pk_mul_f32 v[134:135], v[118:119], v[124:125] op_sel:[0,1] op_sel_hi:[1,1]
	v_pk_mul_f32 v[136:137], v[116:117], v[126:127] op_sel_hi:[1,0]
	v_pk_mul_f32 v[138:139], v[118:119], v[126:127] op_sel:[0,1] op_sel_hi:[1,1]
	v_cvt_pk_bf16_f32 v128, v132, v134
	ds_write_b32 v131, v128 offset:35104
	v_cvt_pk_bf16_f32 v129, v136, v138
	ds_write_b32 v131, v129 offset:53536
	v_cvt_pk_bf16_f32 v128, v133, v135
	ds_write_b32 v131, v128 offset:35248
	v_cvt_pk_bf16_f32 v129, v137, v139
	ds_write_b32 v131, v129 offset:53680
	v_pk_mul_f32 v[132:133], v[112:113], v[124:125] op_sel_hi:[1,0]
	v_pk_mul_f32 v[134:135], v[114:115], v[124:125] op_sel:[0,1] op_sel_hi:[1,1]
	v_pk_mul_f32 v[136:137], v[112:113], v[126:127] op_sel_hi:[1,0]
	v_pk_mul_f32 v[138:139], v[114:115], v[126:127] op_sel:[0,1] op_sel_hi:[1,1]
	v_cvt_pk_bf16_f32 v128, v132, v134
	ds_write_b32 v131, v128 offset:35392
	v_cvt_pk_bf16_f32 v129, v136, v138
	ds_write_b32 v131, v129 offset:53824
	v_cvt_pk_bf16_f32 v128, v133, v135
	ds_write_b32 v131, v128 offset:35536
	v_cvt_pk_bf16_f32 v129, v137, v139
	ds_write_b32 v131, v129 offset:53968
	v_pk_mul_f32 v[132:133], v[108:109], v[124:125] op_sel_hi:[1,0]
	v_pk_mul_f32 v[134:135], v[110:111], v[124:125] op_sel:[0,1] op_sel_hi:[1,1]
	v_pk_mul_f32 v[136:137], v[108:109], v[126:127] op_sel_hi:[1,0]
	v_pk_mul_f32 v[138:139], v[110:111], v[126:127] op_sel:[0,1] op_sel_hi:[1,1]
	v_cvt_pk_bf16_f32 v128, v132, v134
	ds_write_b32 v131, v128 offset:35680
	v_cvt_pk_bf16_f32 v129, v136, v138
	ds_write_b32 v131, v129 offset:54112
	v_cvt_pk_bf16_f32 v128, v133, v135
	ds_write_b32 v131, v128 offset:35824
	v_cvt_pk_bf16_f32 v129, v137, v139
	ds_write_b32 v131, v129 offset:54256
	s_branch .Lgpk1_end
.Lgpk1_rev:
	v_pk_mul_f32 v[132:133], v[120:121], v[124:125] op_sel_hi:[1,0]
	v_pk_mul_f32 v[134:135], v[122:123], v[124:125] op_sel:[0,1] op_sel_hi:[1,1]
	v_pk_mul_f32 v[136:137], v[120:121], v[126:127] op_sel_hi:[1,0]
	v_pk_mul_f32 v[138:139], v[122:123], v[126:127] op_sel:[0,1] op_sel_hi:[1,1]
	v_cvt_pk_bf16_f32 v128, v134, v132
	ds_write_b32 v131, v128 offset:34816
	v_cvt_pk_bf16_f32 v129, v138, v136
	ds_write_b32 v131, v129 offset:53248
	v_cvt_pk_bf16_f32 v128, v135, v133
	ds_write_b32 v131, v128 offset:34960
	v_cvt_pk_bf16_f32 v129, v139, v137
	ds_write_b32 v131, v129 offset:53392
	v_pk_mul_f32 v[132:133], v[116:117], v[124:125] op_sel_hi:[1,0]
	v_pk_mul_f32 v[134:135], v[118:119], v[124:125] op_sel:[0,1] op_sel_hi:[1,1]
	v_pk_mul_f32 v[136:137], v[116:117], v[126:127] op_sel_hi:[1,0]
	v_pk_mul_f32 v[138:139], v[118:119], v[126:127] op_sel:[0,1] op_sel_hi:[1,1]
	v_cvt_pk_bf16_f32 v128, v134, v132
	ds_write_b32 v131, v128 offset:35104
	v_cvt_pk_bf16_f32 v129, v138, v136
	ds_write_b32 v131, v129 offset:53536
	v_cvt_pk_bf16_f32 v128, v135, v133
	ds_write_b32 v131, v128 offset:35248
	v_cvt_pk_bf16_f32 v129, v139, v137
	ds_write_b32 v131, v129 offset:53680
	v_pk_mul_f32 v[132:133], v[112:113], v[124:125] op_sel_hi:[1,0]
	v_pk_mul_f32 v[134:135], v[114:115], v[124:125] op_sel:[0,1] op_sel_hi:[1,1]
	v_pk_mul_f32 v[136:137], v[112:113], v[126:127] op_sel_hi:[1,0]
	v_pk_mul_f32 v[138:139], v[114:115], v[126:127] op_sel:[0,1] op_sel_hi:[1,1]
	v_cvt_pk_bf16_f32 v128, v134, v132
	ds_write_b32 v131, v128 offset:35392
	v_cvt_pk_bf16_f32 v129, v138, v136
	ds_write_b32 v131, v129 offset:53824
	v_cvt_pk_bf16_f32 v128, v135, v133
	ds_write_b32 v131, v128 offset:35536
	v_cvt_pk_bf16_f32 v129, v139, v137
	ds_write_b32 v131, v129 offset:53968
	v_pk_mul_f32 v[132:133], v[108:109], v[124:125] op_sel_hi:[1,0]
	v_pk_mul_f32 v[134:135], v[110:111], v[124:125] op_sel:[0,1] op_sel_hi:[1,1]
	v_pk_mul_f32 v[136:137], v[108:109], v[126:127] op_sel_hi:[1,0]
	v_pk_mul_f32 v[138:139], v[110:111], v[126:127] op_sel:[0,1] op_sel_hi:[1,1]
	v_cvt_pk_bf16_f32 v128, v134, v132
	ds_write_b32 v131, v128 offset:35680
	v_cvt_pk_bf16_f32 v129, v138, v136
	ds_write_b32 v131, v129 offset:54112
	v_cvt_pk_bf16_f32 v128, v135, v133
	ds_write_b32 v131, v128 offset:35824
	v_cvt_pk_bf16_f32 v129, v139, v137
	ds_write_b32 v131, v129 offset:54256
.Lgpk1_end:
	v_lshlrev_b32_e32 v127, 16, v104
	v_lshlrev_b32_e32 v126, 16, v92
	v_and_b32_e32 v125, 0xffff0000, v104
	v_and_b32_e32 v124, 0xffff0000, v92
	v_lshlrev_b32_e32 v129, 16, v105
	v_lshlrev_b32_e32 v128, 16, v93
	v_and_b32_e32 v131, 0xffff0000, v105
	v_and_b32_e32 v130, 0xffff0000, v93
	v_lshlrev_b32_e32 v133, 16, v106
	v_lshlrev_b32_e32 v132, 16, v94
	v_and_b32_e32 v135, 0xffff0000, v106
	v_and_b32_e32 v134, 0xffff0000, v94
	v_lshlrev_b32_e32 v137, 16, v107
	v_lshlrev_b32_e32 v136, 16, v95
	v_and_b32_e32 v139, 0xffff0000, v107
	v_and_b32_e32 v138, 0xffff0000, v95
.LBB0_361:
	s_cmp_lg_u64 s[4:5], 0
	s_cselect_b32 s10, 0, 16
	v_mov_b32_e32 v109, s65
	v_mad_u32_u24 v109, v206, s74, v109
	v_min_u32_e32 v110, v142, v143
	v_lshl_add_u32 v110, v110, 1, v109
	s_waitcnt lgkmcnt(0)
	v_mov_b32_e32 v112, v141
	v_mov_b32_e32 v113, v0
	s_cmp_lg_u64 s[4:5], 0
	s_cbranch_scc0 .Lgpk2_rev
	v_pk_mul_f32 v[114:115], v[126:127], v[112:113]
	v_cvt_pk_bf16_f32 v108, v114, v115
	ds_write_b32 v110, v108 offset:0
	v_pk_mul_f32 v[114:115], v[124:125], v[112:113]
	v_cvt_pk_bf16_f32 v108, v114, v115
	ds_write_b32 v110, v108 offset:144
	v_pk_mul_f32 v[114:115], v[128:129], v[112:113]
	v_cvt_pk_bf16_f32 v108, v114, v115
	ds_write_b32 v110, v108 offset:288
	v_pk_mul_f32 v[114:115], v[130:131], v[112:113]
	v_cvt_pk_bf16_f32 v108, v114, v115
	ds_write_b32 v110, v108 offset:432
	v_pk_mul_f32 v[114:115], v[132:133], v[112:113]
	v_cvt_pk_bf16_f32 v108, v114, v115
	ds_write_b32 v110, v108 offset:576
	v_pk_mul_f32 v[114:115], v[134:135], v[112:113]
	v_cvt_pk_bf16_f32 v108, v114, v115
	ds_write_b32 v110, v108 offset:720
	v_pk_mul_f32 v[114:115], v[136:137], v[112:113]
	v_cvt_pk_bf16_f32 v108, v114, v115
	ds_write_b32 v110, v108 offset:864
	v_pk_mul_f32 v[114:115], v[138:139], v[112:113]
	v_cvt_pk_bf16_f32 v108, v114, v115
	ds_write_b32 v110, v108 offset:1008
	s_branch .Lgpk2_end
.Lgpk2_rev:
	v_pk_mul_f32 v[114:115], v[126:127], v[112:113]
	v_cvt_pk_bf16_f32 v108, v115, v114
	ds_write_b32 v110, v108 offset:0
	v_pk_mul_f32 v[114:115], v[124:125], v[112:113]
	v_cvt_pk_bf16_f32 v108, v115, v114
	ds_write_b32 v110, v108 offset:144
	v_pk_mul_f32 v[114:115], v[128:129], v[112:113]
	v_cvt_pk_bf16_f32 v108, v115, v114
	ds_write_b32 v110, v108 offset:288
	v_pk_mul_f32 v[114:115], v[130:131], v[112:113]
	v_cvt_pk_bf16_f32 v108, v115, v114
	ds_write_b32 v110, v108 offset:432
	v_pk_mul_f32 v[114:115], v[132:133], v[112:113]
	v_cvt_pk_bf16_f32 v108, v115, v114
	ds_write_b32 v110, v108 offset:576
	v_pk_mul_f32 v[114:115], v[134:135], v[112:113]
	v_cvt_pk_bf16_f32 v108, v115, v114
	ds_write_b32 v110, v108 offset:720
	v_pk_mul_f32 v[114:115], v[136:137], v[112:113]
	v_cvt_pk_bf16_f32 v108, v115, v114
	ds_write_b32 v110, v108 offset:864
	v_pk_mul_f32 v[114:115], v[138:139], v[112:113]
	v_cvt_pk_bf16_f32 v108, v115, v114
	ds_write_b32 v110, v108 offset:1008
.Lgpk2_end:
	v_and_b32_e32 v118, 48, v3
	v_add_u32_e32 v0, 0, v118
	v_or_b32_e32 v108, s92, v206
	s_waitcnt lgkmcnt(0)
	s_barrier
	s_add_i32 s10, s94, 1
	s_cmp_ge_u32 s10, s85
	s_cbranch_scc1 .Lgpf_skip
	s_and_b64 vcc, exec, s[6:7]
	s_cbranch_vccz .Lgpf_skip
	s_lshl_b32 s10, s10, 6
	v_add_u32_e32 v228, s10, v140
	v_xad_u32 v229, v228, -1, s80
	v_cndmask_b32_e64 v229, v229, v228, s[4:5]
	v_add_u32_e32 v228, 1, v228
	v_xad_u32 v230, v228, -1, s80
	v_cndmask_b32_e64 v228, v230, v228, s[4:5]
	v_min_i32_e32 v228, v229, v228
	v_add_u32_e32 v228, v228, v177
	v_mad_i64_i32 v[230:231], vcc, v228, s60, v[182:183]
	v_lshlrev_b32_e32 v228, 4, v205
	v_and_b32_e32 v228, 0xf0, v228
	v_mov_b32_e32 v229, 0
	v_lshl_add_u64 v[230:231], v[230:231], 0, v[228:229]
	global_load_dwordx4 v[84:87], v[230:231], off
	global_load_dwordx4 v[88:91], v[230:231], off offset:2048
	v_lshl_add_u64 v[232:233], v[230:231], 0, s[40:41]
	global_load_dwordx4 v[92:95], v[232:233], off offset:-4096
	global_load_dwordx4 v[96:99], v[232:233], off offset:512
	global_load_dwordx4 v[100:103], v[232:233], off offset:2560
	v_lshl_add_u64 v[234:235], v[232:233], 0, s[40:41]
	global_load_dwordx4 v[104:107], v[234:235], off offset:-3584
	v_or_b32_e32 v228, s10, v3
	v_xad_u32 v230, v228, -1, s80
	v_cndmask_b32_e64 v228, v230, v228, s[4:5]
	v_add_u32_e32 v228, v228, v177
	v_mov_b64_e32 v[232:233], s[36:37]
	v_mad_i64_i32 v[232:233], vcc, v228, s60, v[232:233]
	v_mov_b32_e32 v234, v2
	v_mov_b32_e32 v235, 0
	v_lshl_add_u64 v[232:233], v[232:233], 0, v[234:235]
	v_mov_b32_e32 v234, v180
	v_lshl_add_u64 v[232:233], v[232:233], 0, v[234:235]
	v_lshl_add_u64 v[232:233], v[232:233], 0, s[40:41]
	global_load_ushort v181, v[232:233], off
	global_load_ushort v186, v[232:233], off offset:32
.Lgpf_skip:
	v_lshrrev_b32_e32 v207, 4, v3
	v_mul_u32_u24_e32 v116, 0x110, v206
	v_mul_u32_u24_e32 v115, 0x90, v206
	s_mov_b32 s27, 0x1a400
	v_lshlrev_b32_e32 v208, 3, v207
	v_lshlrev_b32_e32 v209, 3, v207
	v_lshl_add_u32 v116, v207, 4, v116
	v_lshl_add_u32 v117, v206, 2, s81
	v_lshl_add_u32 v114, v207, 4, s81
	v_add3_u32 v115, v115, v208, s27
	v_or_b32_e32 v118, s84, v206
	v_lshlrev_b32_e32 v119, 2, v207
	v_mul_u32_u24_e32 v136, 0x140, v207
	v_sub_u32_e32 v119, v206, v119
	v_lshl_add_u32 v136, v206, 2, v136
	v_add_u32_e32 v136, s97, v136
	v_mov_b32_e32 v138, 0x3fb8aa3b
	v_mov_b32_e32 v139, 0x3fb8aa3b
	s_cmp_lt_u32 s79, 4
	s_cbranch_scc1 .Lgt_lo
	s_cmp_lt_u32 s79, 6
	s_cbranch_scc1 .Lgt_45
	s_cmp_eq_u32 s79, 6
	s_cbranch_scc1 .Lgt_w6
	ds_read_b128 v[120:123], v116 offset:17408
	ds_read_b128 v[142:145], v116 offset:30464
	ds_read_b128 v[124:127], v116 offset:17472
	ds_read_b128 v[146:149], v116 offset:30528
	ds_read_b128 v[128:131], v116 offset:17536
	ds_read_b128 v[150:153], v116 offset:30592
	ds_read_b128 v[132:135], v116 offset:17600
	ds_read_b128 v[154:157], v116 offset:30656
	ds_read_b32 v112, v117 offset:192
	ds_read_b32 v113, v117 offset:2240
	ds_read_b128 v[160:163], v114 offset:0
	s_waitcnt lgkmcnt(9)
	v_mfma_f32_16x16x32_bf16 v[108:111], v[120:123], v[142:145], 0
	s_waitcnt lgkmcnt(7)
	v_mfma_f32_16x16x32_bf16 v[108:111], v[124:127], v[146:149], v[108:111]
	s_waitcnt lgkmcnt(5)
	v_mfma_f32_16x16x32_bf16 v[108:111], v[128:131], v[150:153], v[108:111]
	s_waitcnt lgkmcnt(3)
	v_mfma_f32_16x16x32_bf16 v[108:111], v[132:135], v[154:157], v[108:111]
	s_waitcnt lgkmcnt(0)
	v_sub_f32_e32 v164, v112, v160
	v_sub_f32_e32 v165, v112, v161
	v_sub_f32_e32 v166, v112, v162
	v_sub_f32_e32 v167, v112, v163
	v_pk_mul_f32 v[164:165], v[164:165], v[138:139]
	v_pk_mul_f32 v[166:167], v[166:167], v[138:139]
	v_exp_f32_e32 v164, v164
	v_exp_f32_e32 v165, v165
	v_exp_f32_e32 v166, v166
	v_exp_f32_e32 v167, v167
	v_pk_mul_f32 v[108:109], v[108:109], v[112:113] op_sel:[0,1] op_sel_hi:[1,1]
	v_pk_mul_f32 v[110:111], v[110:111], v[112:113] op_sel:[0,1] op_sel_hi:[1,1]
	v_pk_mul_f32 v[108:109], v[108:109], v[164:165]
	v_pk_mul_f32 v[110:111], v[110:111], v[166:167]
	v_cvt_pk_bf16_f32 v168, -v108, -v109
	v_cvt_pk_bf16_f32 v169, -v110, -v111
	ds_write_b64 v115, v[168:169] offset:23808
	ds_read_b128 v[120:123], v116 offset:21760
	ds_read_b128 v[142:145], v116 offset:13056
	ds_read_b128 v[124:127], v116 offset:21824
	ds_read_b128 v[146:149], v116 offset:13120
	ds_read_b128 v[128:131], v116 offset:21888
	ds_read_b128 v[150:153], v116 offset:13184
	ds_read_b128 v[132:135], v116 offset:21952
	ds_read_b128 v[154:157], v116 offset:13248
	ds_read_b32 v112, v117 offset:192
	ds_read_b128 v[160:163], v114 offset:64
	s_waitcnt lgkmcnt(8)
	v_mfma_f32_16x16x32_bf16 v[108:111], v[120:123], v[142:145], 0
	s_waitcnt lgkmcnt(6)
	v_mfma_f32_16x16x32_bf16 v[108:111], v[124:127], v[146:149], v[108:111]
	s_waitcnt lgkmcnt(4)
	v_mfma_f32_16x16x32_bf16 v[108:111], v[128:131], v[150:153], v[108:111]
	s_waitcnt lgkmcnt(2)
	v_mfma_f32_16x16x32_bf16 v[108:111], v[132:135], v[154:157], v[108:111]
	s_waitcnt lgkmcnt(0)
	v_sub_f32_e32 v164, v112, v160
	v_sub_f32_e32 v165, v112, v161
	v_sub_f32_e32 v166, v112, v162
	v_sub_f32_e32 v167, v112, v163
	v_pk_mul_f32 v[164:165], v[164:165], v[138:139]
	v_pk_mul_f32 v[166:167], v[166:167], v[138:139]
	v_exp_f32_e32 v164, v164
	v_exp_f32_e32 v165, v165
	v_exp_f32_e32 v166, v166
	v_exp_f32_e32 v167, v167
	v_pk_mul_f32 v[108:109], v[108:109], v[164:165]
	v_pk_mul_f32 v[110:111], v[110:111], v[166:167]
	v_cvt_pk_bf16_f32 v168, v108, v109
	v_cvt_pk_bf16_f32 v169, v110, v111
	ds_write_b64 v115, v[168:169] offset:6944
	ds_read_b128 v[120:123], v116 offset:26112
	ds_read_b128 v[142:145], v116 offset:13056
	ds_read_b128 v[124:127], v116 offset:26176
	ds_read_b128 v[146:149], v116 offset:13120
	ds_read_b128 v[128:131], v116 offset:26240
	ds_read_b128 v[150:153], v116 offset:13184
	ds_read_b128 v[132:135], v116 offset:26304
	ds_read_b128 v[154:157], v116 offset:13248
	ds_read_b32 v112, v117 offset:192
	ds_read_b128 v[160:163], v114 offset:128
	s_waitcnt lgkmcnt(8)
	v_mfma_f32_16x16x32_bf16 v[108:111], v[120:123], v[142:145], 0
	s_waitcnt lgkmcnt(6)
	v_mfma_f32_16x16x32_bf16 v[108:111], v[124:127], v[146:149], v[108:111]
	s_waitcnt lgkmcnt(4)
	v_mfma_f32_16x16x32_bf16 v[108:111], v[128:131], v[150:153], v[108:111]
	s_waitcnt lgkmcnt(2)
	v_mfma_f32_16x16x32_bf16 v[108:111], v[132:135], v[154:157], v[108:111]
	s_waitcnt lgkmcnt(0)
	v_sub_f32_e32 v164, v112, v160
	v_sub_f32_e32 v165, v112, v161
	v_sub_f32_e32 v166, v112, v162
	v_sub_f32_e32 v167, v112, v163
	v_pk_mul_f32 v[164:165], v[164:165], v[138:139]
	v_pk_mul_f32 v[166:167], v[166:167], v[138:139]
	v_exp_f32_e32 v164, v164
	v_exp_f32_e32 v165, v165
	v_exp_f32_e32 v166, v166
	v_exp_f32_e32 v167, v167
	v_pk_mul_f32 v[108:109], v[108:109], v[164:165]
	v_pk_mul_f32 v[110:111], v[110:111], v[166:167]
	v_cvt_pk_bf16_f32 v168, v108, v109
	v_cvt_pk_bf16_f32 v169, v110, v111
	ds_write_b64 v115, v[168:169] offset:6976
	ds_read_b128 v[120:123], v116 offset:30464
	ds_read_b128 v[142:145], v116 offset:13056
	ds_read_b128 v[124:127], v116 offset:30528
	ds_read_b128 v[146:149], v116 offset:13120
	ds_read_b128 v[128:131], v116 offset:30592
	ds_read_b128 v[150:153], v116 offset:13184
	ds_read_b128 v[132:135], v116 offset:30656
	ds_read_b128 v[154:157], v116 offset:13248
	ds_read_b32 v112, v117 offset:192
	ds_read_b128 v[160:163], v114 offset:192
	v_cmp_le_i32_e64 s[10:11], 0, v119
	v_cmp_le_i32_e64 s[12:13], 1, v119
	v_cmp_le_i32_e64 s[48:49], 2, v119
	v_cmp_le_i32_e64 s[50:51], 3, v119
	s_waitcnt lgkmcnt(8)
	v_mfma_f32_16x16x32_bf16 v[108:111], v[120:123], v[142:145], 0
	s_waitcnt lgkmcnt(6)
	v_mfma_f32_16x16x32_bf16 v[108:111], v[124:127], v[146:149], v[108:111]
	s_waitcnt lgkmcnt(4)
	v_mfma_f32_16x16x32_bf16 v[108:111], v[128:131], v[150:153], v[108:111]
	s_waitcnt lgkmcnt(2)
	v_mfma_f32_16x16x32_bf16 v[108:111], v[132:135], v[154:157], v[108:111]
	s_waitcnt lgkmcnt(0)
	v_sub_f32_e32 v164, v112, v160
	v_sub_f32_e32 v165, v112, v161
	v_sub_f32_e32 v166, v112, v162
	v_sub_f32_e32 v167, v112, v163
	v_pk_mul_f32 v[164:165], v[164:165], v[138:139]
	v_pk_mul_f32 v[166:167], v[166:167], v[138:139]
	v_exp_f32_e32 v164, v164
	v_exp_f32_e32 v165, v165
	v_exp_f32_e32 v166, v166
	v_exp_f32_e32 v167, v167
	v_pk_mul_f32 v[108:109], v[108:109], v[164:165]
	v_pk_mul_f32 v[110:111], v[110:111], v[166:167]
	v_cndmask_b32_e64 v108, 0, v108, s[10:11]
	v_cndmask_b32_e64 v109, 0, v109, s[12:13]
	v_cndmask_b32_e64 v110, 0, v110, s[48:49]
	v_cndmask_b32_e64 v111, 0, v111, s[50:51]
	v_cvt_pk_bf16_f32 v168, v108, v109
	v_cvt_pk_bf16_f32 v169, v110, v111
	ds_write_b64 v115, v[168:169] offset:7008
	s_branch .Lgt_end
.Lgt_w6:
	ds_read_b128 v[120:123], v116 offset:21760
	ds_read_b128 v[142:145], v116 offset:26112
	ds_read_b128 v[124:127], v116 offset:21824
	ds_read_b128 v[146:149], v116 offset:26176
	ds_read_b128 v[128:131], v116 offset:21888
	ds_read_b128 v[150:153], v116 offset:26240
	ds_read_b128 v[132:135], v116 offset:21952
	ds_read_b128 v[154:157], v116 offset:26304
	ds_read_b32 v112, v117 offset:128
	ds_read_b32 v113, v117 offset:2176
	ds_read_b128 v[160:163], v114 offset:64
	s_waitcnt lgkmcnt(9)
	v_mfma_f32_16x16x32_bf16 v[108:111], v[120:123], v[142:145], 0
	s_waitcnt lgkmcnt(7)
	v_mfma_f32_16x16x32_bf16 v[108:111], v[124:127], v[146:149], v[108:111]
	s_waitcnt lgkmcnt(5)
	v_mfma_f32_16x16x32_bf16 v[108:111], v[128:131], v[150:153], v[108:111]
	s_waitcnt lgkmcnt(3)
	v_mfma_f32_16x16x32_bf16 v[108:111], v[132:135], v[154:157], v[108:111]
	s_waitcnt lgkmcnt(0)
	v_sub_f32_e32 v164, v112, v160
	v_sub_f32_e32 v165, v112, v161
	v_sub_f32_e32 v166, v112, v162
	v_sub_f32_e32 v167, v112, v163
	v_pk_mul_f32 v[164:165], v[164:165], v[138:139]
	v_pk_mul_f32 v[166:167], v[166:167], v[138:139]
	v_exp_f32_e32 v164, v164
	v_exp_f32_e32 v165, v165
	v_exp_f32_e32 v166, v166
	v_exp_f32_e32 v167, v167
	v_pk_mul_f32 v[108:109], v[108:109], v[112:113] op_sel:[0,1] op_sel_hi:[1,1]
	v_pk_mul_f32 v[110:111], v[110:111], v[112:113] op_sel:[0,1] op_sel_hi:[1,1]
	v_pk_mul_f32 v[108:109], v[108:109], v[164:165]
	v_pk_mul_f32 v[110:111], v[110:111], v[166:167]
	v_cvt_pk_bf16_f32 v168, -v108, -v109
	v_cvt_pk_bf16_f32 v169, -v110, -v111
	ds_write_b64 v115, v[168:169] offset:21536
	ds_read_b128 v[120:123], v116 offset:21760
	ds_read_b128 v[142:145], v116 offset:8704
	ds_read_b128 v[124:127], v116 offset:21824
	ds_read_b128 v[146:149], v116 offset:8768
	ds_read_b128 v[128:131], v116 offset:21888
	ds_read_b128 v[150:153], v116 offset:8832
	ds_read_b128 v[132:135], v116 offset:21952
	ds_read_b128 v[154:157], v116 offset:8896
	ds_read_b32 v112, v117 offset:128
	ds_read_b128 v[160:163], v114 offset:64
	s_waitcnt lgkmcnt(8)
	v_mfma_f32_16x16x32_bf16 v[108:111], v[120:123], v[142:145], 0
	s_waitcnt lgkmcnt(6)
	v_mfma_f32_16x16x32_bf16 v[108:111], v[124:127], v[146:149], v[108:111]
	s_waitcnt lgkmcnt(4)
	v_mfma_f32_16x16x32_bf16 v[108:111], v[128:131], v[150:153], v[108:111]
	s_waitcnt lgkmcnt(2)
	v_mfma_f32_16x16x32_bf16 v[108:111], v[132:135], v[154:157], v[108:111]
	s_waitcnt lgkmcnt(0)
	v_sub_f32_e32 v164, v112, v160
	v_sub_f32_e32 v165, v112, v161
	v_sub_f32_e32 v166, v112, v162
	v_sub_f32_e32 v167, v112, v163
	v_pk_mul_f32 v[164:165], v[164:165], v[138:139]
	v_pk_mul_f32 v[166:167], v[166:167], v[138:139]
	v_exp_f32_e32 v164, v164
	v_exp_f32_e32 v165, v165
	v_exp_f32_e32 v166, v166
	v_exp_f32_e32 v167, v167
	v_pk_mul_f32 v[108:109], v[108:109], v[164:165]
	v_pk_mul_f32 v[110:111], v[110:111], v[166:167]
	v_cvt_pk_bf16_f32 v168, v108, v109
	v_cvt_pk_bf16_f32 v169, v110, v111
	ds_write_b64 v115, v[168:169] offset:4640
	ds_read_b128 v[120:123], v116 offset:26112
	ds_read_b128 v[142:145], v116 offset:8704
	ds_read_b128 v[124:127], v116 offset:26176
	ds_read_b128 v[146:149], v116 offset:8768
	ds_read_b128 v[128:131], v116 offset:26240
	ds_read_b128 v[150:153], v116 offset:8832
	ds_read_b128 v[132:135], v116 offset:26304
	ds_read_b128 v[154:157], v116 offset:8896
	ds_read_b32 v112, v117 offset:128
	ds_read_b128 v[160:163], v114 offset:128
	v_cmp_le_i32_e64 s[10:11], 0, v119
	v_cmp_le_i32_e64 s[12:13], 1, v119
	v_cmp_le_i32_e64 s[48:49], 2, v119
	v_cmp_le_i32_e64 s[50:51], 3, v119
	s_waitcnt lgkmcnt(8)
	v_mfma_f32_16x16x32_bf16 v[108:111], v[120:123], v[142:145], 0
	s_waitcnt lgkmcnt(6)
	v_mfma_f32_16x16x32_bf16 v[108:111], v[124:127], v[146:149], v[108:111]
	s_waitcnt lgkmcnt(4)
	v_mfma_f32_16x16x32_bf16 v[108:111], v[128:131], v[150:153], v[108:111]
	s_waitcnt lgkmcnt(2)
	v_mfma_f32_16x16x32_bf16 v[108:111], v[132:135], v[154:157], v[108:111]
	s_waitcnt lgkmcnt(0)
	v_sub_f32_e32 v164, v112, v160
	v_sub_f32_e32 v165, v112, v161
	v_sub_f32_e32 v166, v112, v162
	v_sub_f32_e32 v167, v112, v163
	v_pk_mul_f32 v[164:165], v[164:165], v[138:139]
	v_pk_mul_f32 v[166:167], v[166:167], v[138:139]
	v_exp_f32_e32 v164, v164
	v_exp_f32_e32 v165, v165
	v_exp_f32_e32 v166, v166
	v_exp_f32_e32 v167, v167
	v_pk_mul_f32 v[108:109], v[108:109], v[164:165]
	v_pk_mul_f32 v[110:111], v[110:111], v[166:167]
	v_cndmask_b32_e64 v108, 0, v108, s[10:11]
	v_cndmask_b32_e64 v109, 0, v109, s[12:13]
	v_cndmask_b32_e64 v110, 0, v110, s[48:49]
	v_cndmask_b32_e64 v111, 0, v111, s[50:51]
	v_cvt_pk_bf16_f32 v168, v108, v109
	v_cvt_pk_bf16_f32 v169, v110, v111
	ds_write_b64 v115, v[168:169] offset:4672
	ds_read_b128 v[120:123], v116 offset:17408
	ds_read_b128 v[142:145], v116 offset:13056
	ds_read_b128 v[124:127], v116 offset:17472
	ds_read_b128 v[146:149], v116 offset:13120
	ds_read_b128 v[128:131], v116 offset:17536
	ds_read_b128 v[150:153], v116 offset:13184
	ds_read_b128 v[132:135], v116 offset:17600
	ds_read_b128 v[154:157], v116 offset:13248
	ds_read_b32 v112, v117 offset:192
	ds_read_b128 v[160:163], v114 offset:0
	s_waitcnt lgkmcnt(8)
	v_mfma_f32_16x16x32_bf16 v[108:111], v[120:123], v[142:145], 0
	s_waitcnt lgkmcnt(6)
	v_mfma_f32_16x16x32_bf16 v[108:111], v[124:127], v[146:149], v[108:111]
	s_waitcnt lgkmcnt(4)
	v_mfma_f32_16x16x32_bf16 v[108:111], v[128:131], v[150:153], v[108:111]
	s_waitcnt lgkmcnt(2)
	v_mfma_f32_16x16x32_bf16 v[108:111], v[132:135], v[154:157], v[108:111]
	s_waitcnt lgkmcnt(0)
	v_sub_f32_e32 v164, v112, v160
	v_sub_f32_e32 v165, v112, v161
	v_sub_f32_e32 v166, v112, v162
	v_sub_f32_e32 v167, v112, v163
	v_pk_mul_f32 v[164:165], v[164:165], v[138:139]
	v_pk_mul_f32 v[166:167], v[166:167], v[138:139]
	v_exp_f32_e32 v164, v164
	v_exp_f32_e32 v165, v165
	v_exp_f32_e32 v166, v166
	v_exp_f32_e32 v167, v167
	v_pk_mul_f32 v[108:109], v[108:109], v[164:165]
	v_pk_mul_f32 v[110:111], v[110:111], v[166:167]
	v_cvt_pk_bf16_f32 v168, v108, v109
	v_cvt_pk_bf16_f32 v169, v110, v111
	ds_write_b64 v115, v[168:169] offset:6912
	s_branch .Lgt_end
.Lgt_45:
	s_cmp_eq_u32 s79, 4
	s_cbranch_scc1 .Lgt_w4
	ds_read_b128 v[120:123], v116 offset:17408
	ds_read_b128 v[142:145], v116 offset:26112
	ds_read_b128 v[124:127], v116 offset:17472
	ds_read_b128 v[146:149], v116 offset:26176
	ds_read_b128 v[128:131], v116 offset:17536
	ds_read_b128 v[150:153], v116 offset:26240
	ds_read_b128 v[132:135], v116 offset:17600
	ds_read_b128 v[154:157], v116 offset:26304
	ds_read_b32 v112, v117 offset:128
	ds_read_b32 v113, v117 offset:2176
	ds_read_b128 v[160:163], v114 offset:0
	s_waitcnt lgkmcnt(9)
	v_mfma_f32_16x16x32_bf16 v[108:111], v[120:123], v[142:145], 0
	s_waitcnt lgkmcnt(7)
	v_mfma_f32_16x16x32_bf16 v[108:111], v[124:127], v[146:149], v[108:111]
	s_waitcnt lgkmcnt(5)
	v_mfma_f32_16x16x32_bf16 v[108:111], v[128:131], v[150:153], v[108:111]
	s_waitcnt lgkmcnt(3)
	v_mfma_f32_16x16x32_bf16 v[108:111], v[132:135], v[154:157], v[108:111]
	s_waitcnt lgkmcnt(0)
	v_sub_f32_e32 v164, v112, v160
	v_sub_f32_e32 v165, v112, v161
	v_sub_f32_e32 v166, v112, v162
	v_sub_f32_e32 v167, v112, v163
	v_pk_mul_f32 v[164:165], v[164:165], v[138:139]
	v_pk_mul_f32 v[166:167], v[166:167], v[138:139]
	v_exp_f32_e32 v164, v164
	v_exp_f32_e32 v165, v165
	v_exp_f32_e32 v166, v166
	v_exp_f32_e32 v167, v167
	v_pk_mul_f32 v[108:109], v[108:109], v[112:113] op_sel:[0,1] op_sel_hi:[1,1]
	v_pk_mul_f32 v[110:111], v[110:111], v[112:113] op_sel:[0,1] op_sel_hi:[1,1]
	v_pk_mul_f32 v[108:109], v[108:109], v[164:165]
	v_pk_mul_f32 v[110:111], v[110:111], v[166:167]
	v_cvt_pk_bf16_f32 v168, -v108, -v109
	v_cvt_pk_bf16_f32 v169, -v110, -v111
	ds_write_b64 v115, v[168:169] offset:21504
	ds_read_b128 v[120:123], v116 offset:17408
	ds_read_b128 v[142:145], v116 offset:4352
	ds_read_b128 v[124:127], v116 offset:17472
	ds_read_b128 v[146:149], v116 offset:4416
	ds_read_b128 v[128:131], v116 offset:17536
	ds_read_b128 v[150:153], v116 offset:4480
	ds_read_b128 v[132:135], v116 offset:17600
	ds_read_b128 v[154:157], v116 offset:4544
	ds_read_b32 v112, v117 offset:64
	ds_read_b128 v[160:163], v114 offset:0
	s_waitcnt lgkmcnt(8)
	v_mfma_f32_16x16x32_bf16 v[108:111], v[120:123], v[142:145], 0
	s_waitcnt lgkmcnt(6)
	v_mfma_f32_16x16x32_bf16 v[108:111], v[124:127], v[146:149], v[108:111]
	s_waitcnt lgkmcnt(4)
	v_mfma_f32_16x16x32_bf16 v[108:111], v[128:131], v[150:153], v[108:111]
	s_waitcnt lgkmcnt(2)
	v_mfma_f32_16x16x32_bf16 v[108:111], v[132:135], v[154:157], v[108:111]
	s_waitcnt lgkmcnt(0)
	v_sub_f32_e32 v164, v112, v160
	v_sub_f32_e32 v165, v112, v161
	v_sub_f32_e32 v166, v112, v162
	v_sub_f32_e32 v167, v112, v163
	v_pk_mul_f32 v[164:165], v[164:165], v[138:139]
	v_pk_mul_f32 v[166:167], v[166:167], v[138:139]
	v_exp_f32_e32 v164, v164
	v_exp_f32_e32 v165, v165
	v_exp_f32_e32 v166, v166
	v_exp_f32_e32 v167, v167
	v_pk_mul_f32 v[108:109], v[108:109], v[164:165]
	v_pk_mul_f32 v[110:111], v[110:111], v[166:167]
	v_cvt_pk_bf16_f32 v168, v108, v109
	v_cvt_pk_bf16_f32 v169, v110, v111
	ds_write_b64 v115, v[168:169] offset:2304
	ds_read_b128 v[120:123], v116 offset:21760
	ds_read_b128 v[142:145], v116 offset:4352
	ds_read_b128 v[124:127], v116 offset:21824
	ds_read_b128 v[146:149], v116 offset:4416
	ds_read_b128 v[128:131], v116 offset:21888
	ds_read_b128 v[150:153], v116 offset:4480
	ds_read_b128 v[132:135], v116 offset:21952
	ds_read_b128 v[154:157], v116 offset:4544
	ds_read_b32 v112, v117 offset:64
	ds_read_b128 v[160:163], v114 offset:64
	v_cmp_le_i32_e64 s[10:11], 0, v119
	v_cmp_le_i32_e64 s[12:13], 1, v119
	v_cmp_le_i32_e64 s[48:49], 2, v119
	v_cmp_le_i32_e64 s[50:51], 3, v119
	s_waitcnt lgkmcnt(8)
	v_mfma_f32_16x16x32_bf16 v[108:111], v[120:123], v[142:145], 0
	s_waitcnt lgkmcnt(6)
	v_mfma_f32_16x16x32_bf16 v[108:111], v[124:127], v[146:149], v[108:111]
	s_waitcnt lgkmcnt(4)
	v_mfma_f32_16x16x32_bf16 v[108:111], v[128:131], v[150:153], v[108:111]
	s_waitcnt lgkmcnt(2)
	v_mfma_f32_16x16x32_bf16 v[108:111], v[132:135], v[154:157], v[108:111]
	s_waitcnt lgkmcnt(0)
	v_sub_f32_e32 v164, v112, v160
	v_sub_f32_e32 v165, v112, v161
	v_sub_f32_e32 v166, v112, v162
	v_sub_f32_e32 v167, v112, v163
	v_pk_mul_f32 v[164:165], v[164:165], v[138:139]
	v_pk_mul_f32 v[166:167], v[166:167], v[138:139]
	v_exp_f32_e32 v164, v164
	v_exp_f32_e32 v165, v165
	v_exp_f32_e32 v166, v166
	v_exp_f32_e32 v167, v167
	v_pk_mul_f32 v[108:109], v[108:109], v[164:165]
	v_pk_mul_f32 v[110:111], v[110:111], v[166:167]
	v_cndmask_b32_e64 v108, 0, v108, s[10:11]
	v_cndmask_b32_e64 v109, 0, v109, s[12:13]
	v_cndmask_b32_e64 v110, 0, v110, s[48:49]
	v_cndmask_b32_e64 v111, 0, v111, s[50:51]
	v_cvt_pk_bf16_f32 v168, v108, v109
	v_cvt_pk_bf16_f32 v169, v110, v111
	ds_write_b64 v115, v[168:169] offset:2336
	ds_read_b128 v[120:123], v116 offset:17408
	ds_read_b128 v[142:145], v116 offset:8704
	ds_read_b128 v[124:127], v116 offset:17472
	ds_read_b128 v[146:149], v116 offset:8768
	ds_read_b128 v[128:131], v116 offset:17536
	ds_read_b128 v[150:153], v116 offset:8832
	ds_read_b128 v[132:135], v116 offset:17600
	ds_read_b128 v[154:157], v116 offset:8896
	ds_read_b32 v112, v117 offset:128
	ds_read_b128 v[160:163], v114 offset:0
	s_waitcnt lgkmcnt(8)
	v_mfma_f32_16x16x32_bf16 v[108:111], v[120:123], v[142:145], 0
	s_waitcnt lgkmcnt(6)
	v_mfma_f32_16x16x32_bf16 v[108:111], v[124:127], v[146:149], v[108:111]
	s_waitcnt lgkmcnt(4)
	v_mfma_f32_16x16x32_bf16 v[108:111], v[128:131], v[150:153], v[108:111]
	s_waitcnt lgkmcnt(2)
	v_mfma_f32_16x16x32_bf16 v[108:111], v[132:135], v[154:157], v[108:111]
	s_waitcnt lgkmcnt(0)
	v_sub_f32_e32 v164, v112, v160
	v_sub_f32_e32 v165, v112, v161
	v_sub_f32_e32 v166, v112, v162
	v_sub_f32_e32 v167, v112, v163
	v_pk_mul_f32 v[164:165], v[164:165], v[138:139]
	v_pk_mul_f32 v[166:167], v[166:167], v[138:139]
	v_exp_f32_e32 v164, v164
	v_exp_f32_e32 v165, v165
	v_exp_f32_e32 v166, v166
	v_exp_f32_e32 v167, v167
	v_pk_mul_f32 v[108:109], v[108:109], v[164:165]
	v_pk_mul_f32 v[110:111], v[110:111], v[166:167]
	v_cvt_pk_bf16_f32 v168, v108, v109
	v_cvt_pk_bf16_f32 v169, v110, v111
	ds_write_b64 v115, v[168:169] offset:4608
	s_branch .Lgt_end
.Lgt_w4:
	ds_read_b128 v[120:123], v116 offset:17408
	ds_read_b128 v[142:145], v116 offset:21760
	ds_read_b128 v[124:127], v116 offset:17472
	ds_read_b128 v[146:149], v116 offset:21824
	ds_read_b128 v[128:131], v116 offset:17536
	ds_read_b128 v[150:153], v116 offset:21888
	ds_read_b128 v[132:135], v116 offset:17600
	ds_read_b128 v[154:157], v116 offset:21952
	ds_read_b32 v112, v117 offset:64
	ds_read_b32 v113, v117 offset:2112
	ds_read_b128 v[160:163], v114 offset:0
	s_waitcnt lgkmcnt(9)
	v_mfma_f32_16x16x32_bf16 v[108:111], v[120:123], v[142:145], 0
	s_waitcnt lgkmcnt(7)
	v_mfma_f32_16x16x32_bf16 v[108:111], v[124:127], v[146:149], v[108:111]
	s_waitcnt lgkmcnt(5)
	v_mfma_f32_16x16x32_bf16 v[108:111], v[128:131], v[150:153], v[108:111]
	s_waitcnt lgkmcnt(3)
	v_mfma_f32_16x16x32_bf16 v[108:111], v[132:135], v[154:157], v[108:111]
	s_waitcnt lgkmcnt(0)
	v_sub_f32_e32 v164, v112, v160
	v_sub_f32_e32 v165, v112, v161
	v_sub_f32_e32 v166, v112, v162
	v_sub_f32_e32 v167, v112, v163
	v_pk_mul_f32 v[164:165], v[164:165], v[138:139]
	v_pk_mul_f32 v[166:167], v[166:167], v[138:139]
	v_exp_f32_e32 v164, v164
	v_exp_f32_e32 v165, v165
	v_exp_f32_e32 v166, v166
	v_exp_f32_e32 v167, v167
	v_pk_mul_f32 v[108:109], v[108:109], v[112:113] op_sel:[0,1] op_sel_hi:[1,1]
	v_pk_mul_f32 v[110:111], v[110:111], v[112:113] op_sel:[0,1] op_sel_hi:[1,1]
	v_pk_mul_f32 v[108:109], v[108:109], v[164:165]
	v_pk_mul_f32 v[110:111], v[110:111], v[166:167]
	v_cvt_pk_bf16_f32 v168, -v108, -v109
	v_cvt_pk_bf16_f32 v169, -v110, -v111
	ds_write_b64 v115, v[168:169] offset:19200
	ds_read_b128 v[120:123], v116 offset:21760
	ds_read_b128 v[142:145], v116 offset:30464
	ds_read_b128 v[124:127], v116 offset:21824
	ds_read_b128 v[146:149], v116 offset:30528
	ds_read_b128 v[128:131], v116 offset:21888
	ds_read_b128 v[150:153], v116 offset:30592
	ds_read_b128 v[132:135], v116 offset:21952
	ds_read_b128 v[154:157], v116 offset:30656
	ds_read_b32 v112, v117 offset:192
	ds_read_b32 v113, v117 offset:2240
	ds_read_b128 v[160:163], v114 offset:64
	s_waitcnt lgkmcnt(9)
	v_mfma_f32_16x16x32_bf16 v[108:111], v[120:123], v[142:145], 0
	s_waitcnt lgkmcnt(7)
	v_mfma_f32_16x16x32_bf16 v[108:111], v[124:127], v[146:149], v[108:111]
	s_waitcnt lgkmcnt(5)
	v_mfma_f32_16x16x32_bf16 v[108:111], v[128:131], v[150:153], v[108:111]
	s_waitcnt lgkmcnt(3)
	v_mfma_f32_16x16x32_bf16 v[108:111], v[132:135], v[154:157], v[108:111]
	s_waitcnt lgkmcnt(0)
	v_sub_f32_e32 v164, v112, v160
	v_sub_f32_e32 v165, v112, v161
	v_sub_f32_e32 v166, v112, v162
	v_sub_f32_e32 v167, v112, v163
	v_pk_mul_f32 v[164:165], v[164:165], v[138:139]
	v_pk_mul_f32 v[166:167], v[166:167], v[138:139]
	v_exp_f32_e32 v164, v164
	v_exp_f32_e32 v165, v165
	v_exp_f32_e32 v166, v166
	v_exp_f32_e32 v167, v167
	v_pk_mul_f32 v[108:109], v[108:109], v[112:113] op_sel:[0,1] op_sel_hi:[1,1]
	v_pk_mul_f32 v[110:111], v[110:111], v[112:113] op_sel:[0,1] op_sel_hi:[1,1]
	v_pk_mul_f32 v[108:109], v[108:109], v[164:165]
	v_pk_mul_f32 v[110:111], v[110:111], v[166:167]
	v_cvt_pk_bf16_f32 v168, -v108, -v109
	v_cvt_pk_bf16_f32 v169, -v110, -v111
	ds_write_b64 v115, v[168:169] offset:23840
	ds_read_b128 v[120:123], v116 offset:26112
	ds_read_b128 v[142:145], v116 offset:30464
	ds_read_b128 v[124:127], v116 offset:26176
	ds_read_b128 v[146:149], v116 offset:30528
	ds_read_b128 v[128:131], v116 offset:26240
	ds_read_b128 v[150:153], v116 offset:30592
	ds_read_b128 v[132:135], v116 offset:26304
	ds_read_b128 v[154:157], v116 offset:30656
	ds_read_b32 v112, v117 offset:192
	ds_read_b32 v113, v117 offset:2240
	ds_read_b128 v[160:163], v114 offset:128
	s_waitcnt lgkmcnt(9)
	v_mfma_f32_16x16x32_bf16 v[108:111], v[120:123], v[142:145], 0
	s_waitcnt lgkmcnt(7)
	v_mfma_f32_16x16x32_bf16 v[108:111], v[124:127], v[146:149], v[108:111]
	s_waitcnt lgkmcnt(5)
	v_mfma_f32_16x16x32_bf16 v[108:111], v[128:131], v[150:153], v[108:111]
	s_waitcnt lgkmcnt(3)
	v_mfma_f32_16x16x32_bf16 v[108:111], v[132:135], v[154:157], v[108:111]
	s_waitcnt lgkmcnt(0)
	v_sub_f32_e32 v164, v112, v160
	v_sub_f32_e32 v165, v112, v161
	v_sub_f32_e32 v166, v112, v162
	v_sub_f32_e32 v167, v112, v163
	v_pk_mul_f32 v[164:165], v[164:165], v[138:139]
	v_pk_mul_f32 v[166:167], v[166:167], v[138:139]
	v_exp_f32_e32 v164, v164
	v_exp_f32_e32 v165, v165
	v_exp_f32_e32 v166, v166
	v_exp_f32_e32 v167, v167
	v_pk_mul_f32 v[108:109], v[108:109], v[112:113] op_sel:[0,1] op_sel_hi:[1,1]
	v_pk_mul_f32 v[110:111], v[110:111], v[112:113] op_sel:[0,1] op_sel_hi:[1,1]
	v_pk_mul_f32 v[108:109], v[108:109], v[164:165]
	v_pk_mul_f32 v[110:111], v[110:111], v[166:167]
	v_cvt_pk_bf16_f32 v168, -v108, -v109
	v_cvt_pk_bf16_f32 v169, -v110, -v111
	ds_write_b64 v115, v[168:169] offset:23872
	ds_read_b128 v[120:123], v116 offset:17408
	ds_read_b128 v[142:145], v116 offset:0
	ds_read_b128 v[124:127], v116 offset:17472
	ds_read_b128 v[146:149], v116 offset:64
	ds_read_b128 v[128:131], v116 offset:17536
	ds_read_b128 v[150:153], v116 offset:128
	ds_read_b128 v[132:135], v116 offset:17600
	ds_read_b128 v[154:157], v116 offset:192
	ds_read_b32 v112, v117 offset:0
	ds_read_b128 v[160:163], v114 offset:0
	v_cmp_le_i32_e64 s[10:11], 0, v119
	v_cmp_le_i32_e64 s[12:13], 1, v119
	v_cmp_le_i32_e64 s[48:49], 2, v119
	v_cmp_le_i32_e64 s[50:51], 3, v119
	s_waitcnt lgkmcnt(8)
	v_mfma_f32_16x16x32_bf16 v[108:111], v[120:123], v[142:145], 0
	s_waitcnt lgkmcnt(6)
	v_mfma_f32_16x16x32_bf16 v[108:111], v[124:127], v[146:149], v[108:111]
	s_waitcnt lgkmcnt(4)
	v_mfma_f32_16x16x32_bf16 v[108:111], v[128:131], v[150:153], v[108:111]
	s_waitcnt lgkmcnt(2)
	v_mfma_f32_16x16x32_bf16 v[108:111], v[132:135], v[154:157], v[108:111]
	s_waitcnt lgkmcnt(0)
	v_sub_f32_e32 v164, v112, v160
	v_sub_f32_e32 v165, v112, v161
	v_sub_f32_e32 v166, v112, v162
	v_sub_f32_e32 v167, v112, v163
	v_pk_mul_f32 v[164:165], v[164:165], v[138:139]
	v_pk_mul_f32 v[166:167], v[166:167], v[138:139]
	v_exp_f32_e32 v164, v164
	v_exp_f32_e32 v165, v165
	v_exp_f32_e32 v166, v166
	v_exp_f32_e32 v167, v167
	v_pk_mul_f32 v[108:109], v[108:109], v[164:165]
	v_pk_mul_f32 v[110:111], v[110:111], v[166:167]
	v_cndmask_b32_e64 v108, 0, v108, s[10:11]
	v_cndmask_b32_e64 v109, 0, v109, s[12:13]
	v_cndmask_b32_e64 v110, 0, v110, s[48:49]
	v_cndmask_b32_e64 v111, 0, v111, s[50:51]
	v_cvt_pk_bf16_f32 v168, v108, v109
	v_cvt_pk_bf16_f32 v169, v110, v111
	ds_write_b64 v115, v[168:169] offset:0
	s_branch .Lgt_end
.Lgt_lo:
	s_cmp_lt_u32 s79, 2
	s_cbranch_scc1 .Lgt_01
	s_cmp_eq_u32 s79, 2
	s_cbranch_scc1 .Lgt_w2
	ds_read_b128 v[120:123], v116 offset:30464
	ds_read_b128 v[142:145], v116 offset:30464
	ds_read_b128 v[124:127], v116 offset:30528
	ds_read_b128 v[146:149], v116 offset:30528
	ds_read_b128 v[128:131], v116 offset:30592
	ds_read_b128 v[150:153], v116 offset:30592
	ds_read_b128 v[132:135], v116 offset:30656
	ds_read_b128 v[154:157], v116 offset:30656
	ds_read_b32 v112, v117 offset:192
	ds_read_b32 v113, v117 offset:2240
	ds_read_b128 v[160:163], v114 offset:192
	v_cmp_lt_i32_e64 s[10:11], 0, v119
	v_cmp_lt_i32_e64 s[12:13], 1, v119
	v_cmp_lt_i32_e64 s[48:49], 2, v119
	v_cmp_lt_i32_e64 s[50:51], 3, v119
	s_waitcnt lgkmcnt(9)
	v_mfma_f32_16x16x32_bf16 v[108:111], v[120:123], v[142:145], 0
	s_waitcnt lgkmcnt(7)
	v_mfma_f32_16x16x32_bf16 v[108:111], v[124:127], v[146:149], v[108:111]
	s_waitcnt lgkmcnt(5)
	v_mfma_f32_16x16x32_bf16 v[108:111], v[128:131], v[150:153], v[108:111]
	s_waitcnt lgkmcnt(3)
	v_mfma_f32_16x16x32_bf16 v[108:111], v[132:135], v[154:157], v[108:111]
	s_waitcnt lgkmcnt(0)
	v_sub_f32_e32 v164, v112, v160
	v_sub_f32_e32 v165, v112, v161
	v_sub_f32_e32 v166, v112, v162
	v_sub_f32_e32 v167, v112, v163
	v_pk_mul_f32 v[164:165], v[164:165], v[138:139]
	v_pk_mul_f32 v[166:167], v[166:167], v[138:139]
	v_exp_f32_e32 v164, v164
	v_exp_f32_e32 v165, v165
	v_exp_f32_e32 v166, v166
	v_exp_f32_e32 v167, v167
	v_pk_mul_f32 v[108:109], v[108:109], v[112:113] op_sel:[0,1] op_sel_hi:[1,1]
	v_pk_mul_f32 v[110:111], v[110:111], v[112:113] op_sel:[0,1] op_sel_hi:[1,1]
	v_pk_mul_f32 v[108:109], v[108:109], v[164:165]
	v_pk_mul_f32 v[110:111], v[110:111], v[166:167]
	v_cndmask_b32_e64 v108, 0, v108, s[10:11]
	v_cndmask_b32_e64 v109, 0, v109, s[12:13]
	v_cndmask_b32_e64 v110, 0, v110, s[48:49]
	v_cndmask_b32_e64 v111, 0, v111, s[50:51]
	v_cvt_pk_bf16_f32 v168, -v108, -v109
	v_cvt_pk_bf16_f32 v169, -v110, -v111
	ds_write_b64 v115, v[168:169] offset:23904
	ds_write_b32 v136, v108 offset:0
	ds_write_b32 v136, v109 offset:80
	ds_write_b32 v136, v110 offset:160
	ds_write_b32 v136, v111 offset:240
	s_branch .Lgt_inv
.Lgt_w2:
	ds_read_b128 v[120:123], v116 offset:26112
	ds_read_b128 v[142:145], v116 offset:26112
	ds_read_b128 v[124:127], v116 offset:26176
	ds_read_b128 v[146:149], v116 offset:26176
	ds_read_b128 v[128:131], v116 offset:26240
	ds_read_b128 v[150:153], v116 offset:26240
	ds_read_b128 v[132:135], v116 offset:26304
	ds_read_b128 v[154:157], v116 offset:26304
	ds_read_b32 v112, v117 offset:128
	ds_read_b32 v113, v117 offset:2176
	ds_read_b128 v[160:163], v114 offset:128
	v_cmp_lt_i32_e64 s[10:11], 0, v119
	v_cmp_lt_i32_e64 s[12:13], 1, v119
	v_cmp_lt_i32_e64 s[48:49], 2, v119
	v_cmp_lt_i32_e64 s[50:51], 3, v119
	s_waitcnt lgkmcnt(9)
	v_mfma_f32_16x16x32_bf16 v[108:111], v[120:123], v[142:145], 0
	s_waitcnt lgkmcnt(7)
	v_mfma_f32_16x16x32_bf16 v[108:111], v[124:127], v[146:149], v[108:111]
	s_waitcnt lgkmcnt(5)
	v_mfma_f32_16x16x32_bf16 v[108:111], v[128:131], v[150:153], v[108:111]
	s_waitcnt lgkmcnt(3)
	v_mfma_f32_16x16x32_bf16 v[108:111], v[132:135], v[154:157], v[108:111]
	s_waitcnt lgkmcnt(0)
	v_sub_f32_e32 v164, v112, v160
	v_sub_f32_e32 v165, v112, v161
	v_sub_f32_e32 v166, v112, v162
	v_sub_f32_e32 v167, v112, v163
	v_pk_mul_f32 v[164:165], v[164:165], v[138:139]
	v_pk_mul_f32 v[166:167], v[166:167], v[138:139]
	v_exp_f32_e32 v164, v164
	v_exp_f32_e32 v165, v165
	v_exp_f32_e32 v166, v166
	v_exp_f32_e32 v167, v167
	v_pk_mul_f32 v[108:109], v[108:109], v[112:113] op_sel:[0,1] op_sel_hi:[1,1]
	v_pk_mul_f32 v[110:111], v[110:111], v[112:113] op_sel:[0,1] op_sel_hi:[1,1]
	v_pk_mul_f32 v[108:109], v[108:109], v[164:165]
	v_pk_mul_f32 v[110:111], v[110:111], v[166:167]
	v_cndmask_b32_e64 v108, 0, v108, s[10:11]
	v_cndmask_b32_e64 v109, 0, v109, s[12:13]
	v_cndmask_b32_e64 v110, 0, v110, s[48:49]
	v_cndmask_b32_e64 v111, 0, v111, s[50:51]
	v_cvt_pk_bf16_f32 v168, -v108, -v109
	v_cvt_pk_bf16_f32 v169, -v110, -v111
	ds_write_b64 v115, v[168:169] offset:21568
	ds_write_b32 v136, v108 offset:0
	ds_write_b32 v136, v109 offset:80
	ds_write_b32 v136, v110 offset:160
	ds_write_b32 v136, v111 offset:240
	s_branch .Lgt_inv
.Lgt_01:
	s_cmp_eq_u32 s79, 0
	s_cbranch_scc1 .Lgt_w0
	ds_read_b128 v[120:123], v116 offset:21760
	ds_read_b128 v[142:145], v116 offset:21760
	ds_read_b128 v[124:127], v116 offset:21824
	ds_read_b128 v[146:149], v116 offset:21824
	ds_read_b128 v[128:131], v116 offset:21888
	ds_read_b128 v[150:153], v116 offset:21888
	ds_read_b128 v[132:135], v116 offset:21952
	ds_read_b128 v[154:157], v116 offset:21952
	ds_read_b32 v112, v117 offset:64
	ds_read_b32 v113, v117 offset:2112
	ds_read_b128 v[160:163], v114 offset:64
	v_cmp_lt_i32_e64 s[10:11], 0, v119
	v_cmp_lt_i32_e64 s[12:13], 1, v119
	v_cmp_lt_i32_e64 s[48:49], 2, v119
	v_cmp_lt_i32_e64 s[50:51], 3, v119
	s_waitcnt lgkmcnt(9)
	v_mfma_f32_16x16x32_bf16 v[108:111], v[120:123], v[142:145], 0
	s_waitcnt lgkmcnt(7)
	v_mfma_f32_16x16x32_bf16 v[108:111], v[124:127], v[146:149], v[108:111]
	s_waitcnt lgkmcnt(5)
	v_mfma_f32_16x16x32_bf16 v[108:111], v[128:131], v[150:153], v[108:111]
	s_waitcnt lgkmcnt(3)
	v_mfma_f32_16x16x32_bf16 v[108:111], v[132:135], v[154:157], v[108:111]
	s_waitcnt lgkmcnt(0)
	v_sub_f32_e32 v164, v112, v160
	v_sub_f32_e32 v165, v112, v161
	v_sub_f32_e32 v166, v112, v162
	v_sub_f32_e32 v167, v112, v163
	v_pk_mul_f32 v[164:165], v[164:165], v[138:139]
	v_pk_mul_f32 v[166:167], v[166:167], v[138:139]
	v_exp_f32_e32 v164, v164
	v_exp_f32_e32 v165, v165
	v_exp_f32_e32 v166, v166
	v_exp_f32_e32 v167, v167
	v_pk_mul_f32 v[108:109], v[108:109], v[112:113] op_sel:[0,1] op_sel_hi:[1,1]
	v_pk_mul_f32 v[110:111], v[110:111], v[112:113] op_sel:[0,1] op_sel_hi:[1,1]
	v_pk_mul_f32 v[108:109], v[108:109], v[164:165]
	v_pk_mul_f32 v[110:111], v[110:111], v[166:167]
	v_cndmask_b32_e64 v108, 0, v108, s[10:11]
	v_cndmask_b32_e64 v109, 0, v109, s[12:13]
	v_cndmask_b32_e64 v110, 0, v110, s[48:49]
	v_cndmask_b32_e64 v111, 0, v111, s[50:51]
	v_cvt_pk_bf16_f32 v168, -v108, -v109
	v_cvt_pk_bf16_f32 v169, -v110, -v111
	ds_write_b64 v115, v[168:169] offset:19232
	ds_write_b32 v136, v108 offset:0
	ds_write_b32 v136, v109 offset:80
	ds_write_b32 v136, v110 offset:160
	ds_write_b32 v136, v111 offset:240
	s_branch .Lgt_inv
.Lgt_w0:
	ds_read_b128 v[120:123], v116 offset:17408
	ds_read_b128 v[142:145], v116 offset:17408
	ds_read_b128 v[124:127], v116 offset:17472
	ds_read_b128 v[146:149], v116 offset:17472
	ds_read_b128 v[128:131], v116 offset:17536
	ds_read_b128 v[150:153], v116 offset:17536
	ds_read_b128 v[132:135], v116 offset:17600
	ds_read_b128 v[154:157], v116 offset:17600
	ds_read_b32 v112, v117 offset:0
	ds_read_b32 v113, v117 offset:2048
	ds_read_b128 v[160:163], v114 offset:0
	v_cmp_lt_i32_e64 s[10:11], 0, v119
	v_cmp_lt_i32_e64 s[12:13], 1, v119
	v_cmp_lt_i32_e64 s[48:49], 2, v119
	v_cmp_lt_i32_e64 s[50:51], 3, v119
	s_waitcnt lgkmcnt(9)
	v_mfma_f32_16x16x32_bf16 v[108:111], v[120:123], v[142:145], 0
	s_waitcnt lgkmcnt(7)
	v_mfma_f32_16x16x32_bf16 v[108:111], v[124:127], v[146:149], v[108:111]
	s_waitcnt lgkmcnt(5)
	v_mfma_f32_16x16x32_bf16 v[108:111], v[128:131], v[150:153], v[108:111]
	s_waitcnt lgkmcnt(3)
	v_mfma_f32_16x16x32_bf16 v[108:111], v[132:135], v[154:157], v[108:111]
	s_waitcnt lgkmcnt(0)
	v_sub_f32_e32 v164, v112, v160
	v_sub_f32_e32 v165, v112, v161
	v_sub_f32_e32 v166, v112, v162
	v_sub_f32_e32 v167, v112, v163
	v_pk_mul_f32 v[164:165], v[164:165], v[138:139]
	v_pk_mul_f32 v[166:167], v[166:167], v[138:139]
	v_exp_f32_e32 v164, v164
	v_exp_f32_e32 v165, v165
	v_exp_f32_e32 v166, v166
	v_exp_f32_e32 v167, v167
	v_pk_mul_f32 v[108:109], v[108:109], v[112:113] op_sel:[0,1] op_sel_hi:[1,1]
	v_pk_mul_f32 v[110:111], v[110:111], v[112:113] op_sel:[0,1] op_sel_hi:[1,1]
	v_pk_mul_f32 v[108:109], v[108:109], v[164:165]
	v_pk_mul_f32 v[110:111], v[110:111], v[166:167]
	v_cndmask_b32_e64 v108, 0, v108, s[10:11]
	v_cndmask_b32_e64 v109, 0, v109, s[12:13]
	v_cndmask_b32_e64 v110, 0, v110, s[48:49]
	v_cndmask_b32_e64 v111, 0, v111, s[50:51]
	v_cvt_pk_bf16_f32 v168, -v108, -v109
	v_cvt_pk_bf16_f32 v169, -v110, -v111
	ds_write_b64 v115, v[168:169] offset:16896
	ds_write_b32 v136, v108 offset:0
	ds_write_b32 v136, v109 offset:80
	ds_write_b32 v136, v110 offset:160
	ds_write_b32 v136, v111 offset:240
